# P0 h1=rmsnorm(x): attn_norm gain quarters 1-3 requested together with the row loads (were one load/vmcnt(0) round trip after each store group)
# baseline (speedup 1.0000x reference)
.LBB0_52:
	s_or_b64 exec, exec, s[24:25]
	v_add_u32_e32 v4, 0xffffc000, v52
	v_cmp_gt_i32_e32 vcc, s2, v52
	v_lshl_add_u64 v[46:47], v[2:3], 0, v[54:55]
	global_load_dwordx4 v[30:33], v[46:47], off
	v_cndmask_b32_e32 v5, 0, v53, vcc
	v_cndmask_b32_e32 v4, v4, v52, vcc
	v_cndmask_b32_e32 v7, v76, v77, vcc
	v_cndmask_b32_e32 v6, v78, v79, vcc
	v_lshlrev_b64 v[2:3], 12, v[4:5]
	v_lshl_add_u64 v[2:3], v[6:7], 0, v[2:3]
	v_lshl_add_u64 v[2:3], v[2:3], 0, v[54:55]
	global_load_dwordx4 v[42:45], v[2:3], off
	global_load_dwordx4 v[22:25], v[2:3], off offset:1024
	global_load_dwordx4 v[10:13], v[2:3], off offset:2048
	s_nop 0
	global_load_dwordx4 v[2:5], v[2:3], off offset:3072
	v_add_u32_e32 v68, s8, v52
	v_add_u32_e32 v6, 0xffffc000, v68
	v_ashrrev_i32_e32 v69, 31, v68
	v_cmp_gt_i32_e32 vcc, s2, v68
	v_lshlrev_b64 v[66:67], 11, v[66:67]
	v_lshl_add_u64 v[52:53], v[52:53], 0, s[12:13]
	v_cndmask_b32_e32 v7, 0, v69, vcc
	v_cndmask_b32_e32 v6, v6, v68, vcc
	v_cndmask_b32_e32 v9, v76, v77, vcc
	v_cndmask_b32_e32 v8, v78, v79, vcc
	v_lshlrev_b64 v[6:7], 12, v[6:7]
	v_lshl_add_u64 v[6:7], v[8:9], 0, v[6:7]
	v_lshl_add_u64 v[14:15], v[6:7], 0, v[54:55]
	global_load_dwordx4 v[38:41], v[14:15], off
	global_load_dwordx4 v[26:29], v[14:15], off offset:1024
	global_load_dwordx4 v[6:9], v[14:15], off offset:3072
	s_nop 0
	global_load_dwordx4 v[14:17], v[14:15], off offset:2048
	s_nop 0
	global_load_dwordx4 v[18:21], v[46:47], off offset:1024
	global_load_dwordx4 v[34:37], v[46:47], off offset:3072
	s_nop 0
	global_load_dwordx4 v[46:49], v[46:47], off offset:2048
	s_nop 0
	global_load_dwordx4 v[80:83], v[56:57], off
	global_load_dwordx4 v[120:123], v[56:57], off offset:1024
	global_load_dwordx4 v[124:127], v[56:57], off offset:2048
	global_load_dwordx4 v[128:131], v[56:57], off offset:3072
	v_lshlrev_b64 v[68:69], 11, v[68:69]
	s_waitcnt vmcnt(15)
	v_pk_mul_f32 v[84:85], v[32:33], v[32:33]
	v_pk_mul_f32 v[86:87], v[30:31], v[30:31]
	s_waitcnt vmcnt(14)
	v_pk_mul_f32 v[90:91], v[42:43], v[42:43]
	v_pk_mov_b32 v[88:89], v[86:87], v[84:85] op_sel:[1,0]
	v_mov_b32_e32 v87, v85
	v_pk_mul_f32 v[84:85], v[44:45], v[44:45]
	s_waitcnt vmcnt(13)
	v_pk_mul_f32 v[92:93], v[24:25], v[24:25]
	v_pk_mul_f32 v[94:95], v[22:23], v[22:23]
	v_pk_mov_b32 v[98:99], v[90:91], v[84:85] op_sel:[1,0]
	v_mov_b32_e32 v91, v85
	v_pk_mov_b32 v[84:85], v[94:95], v[92:93] op_sel:[1,0]
	v_mov_b32_e32 v95, v93
	s_waitcnt vmcnt(12)
	v_mul_f32_e32 v60, v11, v11
	v_mul_f32_e32 v96, v13, v13
	v_pk_add_f32 v[90:91], v[98:99], v[90:91]
	v_pk_add_f32 v[84:85], v[84:85], v[94:95]
	s_waitcnt vmcnt(11)
	v_mul_f32_e32 v109, v4, v4
	v_mul_f32_e32 v110, v5, v5
	v_mul_f32_e32 v111, v2, v2
	v_mul_f32_e32 v112, v3, v3
	v_pk_fma_f32 v[92:93], v[10:11], v[10:11], v[60:61] op_sel_hi:[1,1,0]
	v_pk_fma_f32 v[96:97], v[12:13], v[12:13], v[96:97] op_sel_hi:[1,1,0]
	s_waitcnt vmcnt(10)
	v_pk_mul_f32 v[100:101], v[40:41], v[40:41]
	v_pk_mul_f32 v[102:103], v[38:39], v[38:39]
	s_waitcnt vmcnt(9)
	v_pk_mul_f32 v[104:105], v[28:29], v[28:29]
	v_pk_mul_f32 v[106:107], v[26:27], v[26:27]
	v_pk_add_f32 v[90:91], v[90:91], v[90:91] op_sel:[0,1] op_sel_hi:[1,0]
	v_pk_add_f32 v[84:85], v[84:85], v[84:85] op_sel:[0,1] op_sel_hi:[1,0]
	v_mov_b32_e32 v93, v109
	v_mov_b32_e32 v97, v110
	v_pk_mov_b32 v[94:95], v[102:103], v[100:101] op_sel:[1,0]
	v_mov_b32_e32 v103, v101
	v_pk_mov_b32 v[98:99], v[106:107], v[104:105] op_sel:[1,0]
	v_mov_b32_e32 v107, v105
	v_mov_b32_e32 v91, v111
	v_mov_b32_e32 v85, v112
	v_pk_add_f32 v[92:93], v[92:93], v[96:97]
	v_pk_add_f32 v[94:95], v[94:95], v[102:103]
	v_pk_add_f32 v[96:97], v[98:99], v[106:107]
	v_pk_add_f32 v[84:85], v[90:91], v[84:85]
	s_waitcnt vmcnt(7)
	v_mul_f32_e32 v60, v15, v15
	v_mul_f32_e32 v108, v17, v17
	v_mul_f32_e32 v115, v6, v6
	v_mul_f32_e32 v116, v7, v7
	v_pk_add_f32 v[94:95], v[94:95], v[94:95] op_sel:[0,1] op_sel_hi:[1,0]
	v_pk_add_f32 v[96:97], v[96:97], v[96:97] op_sel:[0,1] op_sel_hi:[1,0]
	v_pk_add_f32 v[84:85], v[84:85], v[92:93]
	v_mul_f32_e32 v113, v8, v8
	v_mul_f32_e32 v114, v9, v9
	v_pk_fma_f32 v[100:101], v[14:15], v[14:15], v[60:61] op_sel_hi:[1,1,0]
	v_pk_fma_f32 v[104:105], v[16:17], v[16:17], v[108:109] op_sel_hi:[1,1,0]
	v_mov_b32_e32 v95, v115
	v_mov_b32_e32 v97, v116
	v_add_f32_e32 v60, v84, v85
	v_mov_b32_e32 v101, v113
	v_mov_b32_e32 v105, v114
	v_pk_add_f32 v[90:91], v[94:95], v[96:97]
	ds_bpermute_b32 v94, v70, v60
	v_pk_add_f32 v[98:99], v[100:101], v[104:105]
	v_pk_add_f32 v[86:87], v[88:89], v[86:87]
	v_pk_add_f32 v[84:85], v[90:91], v[98:99]
	s_waitcnt vmcnt(6)
	v_pk_mul_f32 v[88:89], v[20:21], v[20:21]
	v_pk_mul_f32 v[90:91], v[18:19], v[18:19]
	v_pk_add_f32 v[86:87], v[86:87], v[86:87] op_sel:[0,1] op_sel_hi:[1,0]
	v_pk_mov_b32 v[92:93], v[90:91], v[88:89] op_sel:[1,0]
	v_mov_b32_e32 v91, v89
	v_pk_add_f32 v[88:89], v[92:93], v[90:91]
	s_waitcnt vmcnt(5)
	v_mul_f32_e32 v90, v34, v34
	v_mul_f32_e32 v91, v35, v35
	v_mov_b32_e32 v87, v90
	v_pk_add_f32 v[88:89], v[88:89], v[88:89] op_sel:[0,1] op_sel_hi:[1,0]
	s_waitcnt lgkmcnt(0)
	v_add_f32_e32 v90, v60, v94
	v_mov_b32_e32 v89, v91
	ds_bpermute_b32 v91, v71, v90
	s_waitcnt vmcnt(4)
	v_mul_f32_e32 v60, v47, v47
	v_mul_f32_e32 v92, v36, v36
	v_pk_add_f32 v[86:87], v[86:87], v[88:89]
	v_pk_fma_f32 v[88:89], v[46:47], v[46:47], v[60:61] op_sel_hi:[1,1,0]
	v_mul_f32_e32 v60, v49, v49
	v_mul_f32_e32 v93, v37, v37
	v_mov_b32_e32 v89, v92
	s_waitcnt lgkmcnt(0)
	v_add_f32_e32 v92, v90, v91
	v_pk_fma_f32 v[90:91], v[48:49], v[48:49], v[60:61] op_sel_hi:[1,1,0]
	ds_bpermute_b32 v94, v72, v92
	v_mov_b32_e32 v91, v93
	v_pk_add_f32 v[88:89], v[88:89], v[90:91]
	s_waitcnt lgkmcnt(0)
	v_add_f32_e32 v60, v92, v94
	v_pk_add_f32 v[86:87], v[86:87], v[88:89]
	v_mov_b32_e32 v89, v84
	v_mov_b32_e32 v88, v86
	v_mov_b32_e32 v84, v87
	v_pk_add_f32 v[84:85], v[88:89], v[84:85]
	ds_bpermute_b32 v87, v70, v85
	ds_bpermute_b32 v86, v70, v84
	ds_bpermute_b32 v90, v73, v60
	s_waitcnt lgkmcnt(1)
	v_pk_add_f32 v[84:85], v[84:85], v[86:87]
	ds_bpermute_b32 v87, v71, v85
	ds_bpermute_b32 v86, v71, v84
	s_waitcnt lgkmcnt(2)
	v_add_f32_e32 v60, v60, v90
	ds_bpermute_b32 v88, v74, v60
	s_waitcnt lgkmcnt(1)
	v_pk_add_f32 v[84:85], v[84:85], v[86:87]
	ds_bpermute_b32 v87, v72, v85
	ds_bpermute_b32 v86, v72, v84
	s_waitcnt lgkmcnt(2)
	v_add_f32_e32 v60, v60, v88
	ds_bpermute_b32 v88, v75, v60
	s_waitcnt lgkmcnt(1)
	v_pk_add_f32 v[84:85], v[84:85], v[86:87]
	ds_bpermute_b32 v87, v73, v85
	ds_bpermute_b32 v86, v73, v84
	s_waitcnt lgkmcnt(2)
	v_add_f32_e32 v60, v60, v88
	v_fmamk_f32 v60, v60, 0x3a800000, v64
	v_mul_f32_e32 v88, 0x4b800000, v60
	v_cmp_gt_f32_e32 vcc, s3, v60
	s_waitcnt lgkmcnt(0)
	v_pk_add_f32 v[84:85], v[84:85], v[86:87]
	ds_bpermute_b32 v87, v74, v85
	ds_bpermute_b32 v86, v74, v84
	v_cndmask_b32_e32 v60, v60, v88, vcc
	v_rsq_f32_e32 v60, v60
	s_waitcnt lgkmcnt(0)
	v_pk_add_f32 v[84:85], v[84:85], v[86:87]
	ds_bpermute_b32 v87, v75, v85
	ds_bpermute_b32 v86, v75, v84
	v_mul_f32_e32 v88, 0x45800000, v60
	v_cndmask_b32_e32 v60, v60, v88, vcc
	v_pk_mul_f32 v[42:43], v[42:43], v[60:61] op_sel_hi:[1,0]
	v_pk_mul_f32 v[44:45], v[44:45], v[60:61] op_sel_hi:[1,0]
	s_waitcnt lgkmcnt(0)
	v_pk_add_f32 v[84:85], v[84:85], v[86:87]
	s_waitcnt vmcnt(0)
	v_pk_mul_f32 v[42:43], v[80:81], v[42:43]
	v_pk_fma_f32 v[84:85], v[84:85], s[18:19], v[64:65] op_sel_hi:[1,0,0]
	v_cvt_pk_bf16_f32 v42, v42, v43
	v_mul_f32_e32 v43, 0x4b800000, v85
	v_cmp_gt_f32_e32 vcc, s3, v85
	v_pk_mul_f32 v[44:45], v[82:83], v[44:45]
	v_pk_mul_f32 v[22:23], v[22:23], v[60:61] op_sel_hi:[1,0]
	v_cndmask_b32_e32 v43, v85, v43, vcc
	v_rsq_f32_e32 v85, v43
	v_cvt_pk_bf16_f32 v43, v44, v45
	global_store_dwordx2 v[62:63], v[42:43], off
	v_lshl_add_u64 v[42:43], v[58:59], 0, v[68:69]
	v_mul_f32_e32 v44, 0x45800000, v85
	v_cndmask_b32_e32 v44, v85, v44, vcc
	v_pk_mul_f32 v[38:39], v[38:39], v[44:45] op_sel_hi:[1,0]
	v_pk_mul_f32 v[40:41], v[40:41], v[44:45] op_sel_hi:[1,0]
	v_mul_f32_e32 v45, 0x4b800000, v84
	v_cmp_gt_f32_e32 vcc, s3, v84
	v_pk_mul_f32 v[40:41], v[82:83], v[40:41]
	v_pk_mul_f32 v[38:39], v[80:81], v[38:39]
	v_cndmask_b32_e32 v45, v84, v45, vcc
	v_rsq_f32_e32 v45, v45
	v_cvt_pk_bf16_f32 v38, v38, v39
	v_cvt_pk_bf16_f32 v39, v40, v41
	global_store_dwordx2 v[42:43], v[38:39], off
	v_mul_f32_e32 v38, 0x45800000, v45
	v_cndmask_b32_e32 v38, v45, v38, vcc
	v_pk_mul_f32 v[30:31], v[30:31], v[38:39] op_sel_hi:[1,0]
	v_pk_mul_f32 v[32:33], v[32:33], v[38:39] op_sel_hi:[1,0]
	v_pk_mul_f32 v[30:31], v[80:81], v[30:31]
	v_pk_mul_f32 v[32:33], v[82:83], v[32:33]
	v_cvt_pk_bf16_f32 v30, v30, v31
	v_cvt_pk_bf16_f32 v31, v32, v33
	v_lshl_add_u64 v[40:41], v[58:59], 0, v[66:67]
	global_store_dwordx2 v[40:41], v[30:31], off
	v_pk_mul_f32 v[24:25], v[24:25], v[60:61] op_sel_hi:[1,0]
	v_pk_mul_f32 v[26:27], v[26:27], v[44:45] op_sel_hi:[1,0]
	v_pk_mul_f32 v[28:29], v[28:29], v[44:45] op_sel_hi:[1,0]
	v_pk_mul_f32 v[18:19], v[18:19], v[38:39] op_sel_hi:[1,0]
	v_pk_mul_f32 v[20:21], v[20:21], v[38:39] op_sel_hi:[1,0]
	v_pk_mul_f32 v[10:11], v[10:11], v[60:61] op_sel_hi:[1,0]
	v_pk_mul_f32 v[12:13], v[12:13], v[60:61] op_sel_hi:[1,0]
	v_pk_mul_f32 v[14:15], v[14:15], v[44:45] op_sel_hi:[1,0]
	v_pk_mul_f32 v[16:17], v[16:17], v[44:45] op_sel_hi:[1,0]
	v_pk_mul_f32 v[2:3], v[2:3], v[60:61] op_sel_hi:[1,0]
	v_pk_mul_f32 v[4:5], v[4:5], v[60:61] op_sel_hi:[1,0]
	v_pk_mul_f32 v[6:7], v[6:7], v[44:45] op_sel_hi:[1,0]
	v_pk_mul_f32 v[8:9], v[8:9], v[44:45] op_sel_hi:[1,0]
	v_pk_mul_f32 v[24:25], v[122:123], v[24:25]
	v_pk_mul_f32 v[22:23], v[120:121], v[22:23]
	v_pk_mul_f32 v[28:29], v[122:123], v[28:29]
	v_pk_mul_f32 v[26:27], v[120:121], v[26:27]
	v_pk_mul_f32 v[20:21], v[122:123], v[20:21]
	v_pk_mul_f32 v[18:19], v[120:121], v[18:19]
	v_cvt_pk_bf16_f32 v22, v22, v23
	v_cvt_pk_bf16_f32 v23, v24, v25
	v_cvt_pk_bf16_f32 v24, v26, v27
	v_cvt_pk_bf16_f32 v25, v28, v29
	v_cvt_pk_bf16_f32 v18, v18, v19
	v_cvt_pk_bf16_f32 v19, v20, v21
	global_store_dwordx2 v[62:63], v[22:23], off offset:512
	global_store_dwordx2 v[42:43], v[24:25], off offset:512
	global_store_dwordx2 v[40:41], v[18:19], off offset:512
	v_pk_mul_f32 v[22:23], v[46:47], v[38:39] op_sel_hi:[1,0]
	v_pk_mul_f32 v[24:25], v[48:49], v[38:39] op_sel_hi:[1,0]
	v_pk_mul_f32 v[12:13], v[126:127], v[12:13]
	v_pk_mul_f32 v[10:11], v[124:125], v[10:11]
	v_pk_mul_f32 v[16:17], v[126:127], v[16:17]
	v_pk_mul_f32 v[14:15], v[124:125], v[14:15]
	v_pk_mul_f32 v[20:21], v[126:127], v[24:25]
	v_pk_mul_f32 v[18:19], v[124:125], v[22:23]
	v_cvt_pk_bf16_f32 v10, v10, v11
	v_cvt_pk_bf16_f32 v11, v12, v13
	v_cvt_pk_bf16_f32 v12, v14, v15
	v_cvt_pk_bf16_f32 v13, v16, v17
	v_cvt_pk_bf16_f32 v14, v18, v19
	v_cvt_pk_bf16_f32 v15, v20, v21
	global_store_dwordx2 v[62:63], v[10:11], off offset:1024
	global_store_dwordx2 v[42:43], v[12:13], off offset:1024
	global_store_dwordx2 v[40:41], v[14:15], off offset:1024
	v_add_u32_e32 v14, s0, v52
	v_cmp_lt_i32_e32 vcc, s4, v14
	v_pk_mul_f32 v[14:15], v[34:35], v[38:39] op_sel_hi:[1,0]
	v_pk_mul_f32 v[16:17], v[36:37], v[38:39] op_sel_hi:[1,0]
	s_or_b64 s[14:15], vcc, s[14:15]
	v_pk_mul_f32 v[4:5], v[4:5], v[130:131]
	v_pk_mul_f32 v[2:3], v[2:3], v[128:129]
	v_pk_mul_f32 v[8:9], v[8:9], v[130:131]
	v_pk_mul_f32 v[6:7], v[6:7], v[128:129]
	v_pk_mul_f32 v[12:13], v[16:17], v[130:131]
	v_pk_mul_f32 v[10:11], v[14:15], v[128:129]
	v_cvt_pk_bf16_f32 v2, v2, v3
	v_cvt_pk_bf16_f32 v3, v4, v5
	v_cvt_pk_bf16_f32 v4, v6, v7
	v_cvt_pk_bf16_f32 v5, v8, v9
	v_cvt_pk_bf16_f32 v6, v10, v11
	v_cvt_pk_bf16_f32 v7, v12, v13
	global_store_dwordx2 v[62:63], v[2:3], off offset:1536
	global_store_dwordx2 v[42:43], v[4:5], off offset:1536
	global_store_dwordx2 v[40:41], v[6:7], off offset:1536
	v_lshl_add_u64 v[62:63], v[62:63], 0, s[16:17]
	s_andn2_b64 exec, exec, s[14:15]
	s_cbranch_execz .LBB0_57
